# P1 slack conversion: w_gate and w_branch items (3 of ~7 per wave) with 32 loads in flight
# baseline (speedup 1.0000x reference)
; __device__ __forceinline__ void tr_item(const float* W, int N, int k0, int n0, bf16* WT, int dst_pitch, int dst_row0, int dst_k0, int ncopies, int copy_stride, LAS float* scr, int lane) {
; #pragma unroll 8
;     for (int i = 0; i < 32; ++i) { const int kk = 2 * i + (lane >> 5); scr[kk * 33 + (lane & 31)] = __builtin_nontemporal_load(W + (size_t)(k0 + kk) * N + n0 + (lane & 31)); }
.LBB0_194:
	v_add_u32_e32 v31, s4, v20
	v_add_u32_e32 v30, 6, v31
	v_add_u32_e32 v32, 8, v31
	v_add_u32_e32 v34, 10, v31
	v_add_u32_e32 v50, 12, v31
	v_add_u32_e32 v52, 14, v31
	v_ashrrev_i32_e32 v31, 31, v30
	v_ashrrev_i32_e32 v33, 31, v32
	v_ashrrev_i32_e32 v35, 31, v34
	v_ashrrev_i32_e32 v51, 31, v50
	v_ashrrev_i32_e32 v53, 31, v52
	v_lshlrev_b64 v[30:31], 12, v[30:31]
	v_lshlrev_b64 v[32:33], 12, v[32:33]
	v_lshlrev_b64 v[34:35], 12, v[34:35]
	v_lshlrev_b64 v[50:51], 12, v[50:51]
	v_lshlrev_b64 v[52:53], 12, v[52:53]
	v_lshl_add_u64 v[30:31], v[28:29], 0, v[30:31]
	v_lshl_add_u64 v[32:33], v[28:29], 0, v[32:33]
	v_lshl_add_u64 v[34:35], v[28:29], 0, v[34:35]
	global_load_dword v176, v[26:27], off nt
	global_load_dword v177, v[24:25], off nt
	global_load_dword v178, v[22:23], off nt
	v_lshl_add_u64 v[50:51], v[28:29], 0, v[50:51]
	v_lshl_add_u64 v[52:53], v[28:29], 0, v[52:53]
	global_load_dword v179, v[30:31], off nt
	global_load_dword v180, v[32:33], off nt
	global_load_dword v181, v[34:35], off nt
	global_load_dword v182, v[50:51], off nt
	global_load_dword v183, v[52:53], off nt
	s_add_i32 s4, s4, 16
	v_lshl_add_u64 v[22:23], v[22:23], 0, s[8:9]
	v_lshl_add_u64 v[24:25], v[24:25], 0, s[8:9]
	v_lshl_add_u64 v[26:27], v[26:27], 0, s[8:9]
	v_add_u32_e32 v31, s4, v20
	v_add_u32_e32 v30, 6, v31
	v_add_u32_e32 v32, 8, v31
	v_add_u32_e32 v34, 10, v31
	v_add_u32_e32 v50, 12, v31
	v_add_u32_e32 v52, 14, v31
	v_ashrrev_i32_e32 v31, 31, v30
	v_ashrrev_i32_e32 v33, 31, v32
	v_ashrrev_i32_e32 v35, 31, v34
	v_ashrrev_i32_e32 v51, 31, v50
	v_ashrrev_i32_e32 v53, 31, v52
	v_lshlrev_b64 v[30:31], 12, v[30:31]
	v_lshlrev_b64 v[32:33], 12, v[32:33]
	v_lshlrev_b64 v[34:35], 12, v[34:35]
	v_lshlrev_b64 v[50:51], 12, v[50:51]
	v_lshlrev_b64 v[52:53], 12, v[52:53]
	v_lshl_add_u64 v[30:31], v[28:29], 0, v[30:31]
	v_lshl_add_u64 v[32:33], v[28:29], 0, v[32:33]
	v_lshl_add_u64 v[34:35], v[28:29], 0, v[34:35]
	global_load_dword v184, v[26:27], off nt
	global_load_dword v185, v[24:25], off nt
	global_load_dword v186, v[22:23], off nt
	v_lshl_add_u64 v[50:51], v[28:29], 0, v[50:51]
	v_lshl_add_u64 v[52:53], v[28:29], 0, v[52:53]
	global_load_dword v187, v[30:31], off nt
	global_load_dword v188, v[32:33], off nt
	global_load_dword v189, v[34:35], off nt
	global_load_dword v190, v[50:51], off nt
	global_load_dword v191, v[52:53], off nt
	s_add_i32 s4, s4, 16
	v_lshl_add_u64 v[22:23], v[22:23], 0, s[8:9]
	v_lshl_add_u64 v[24:25], v[24:25], 0, s[8:9]
	v_lshl_add_u64 v[26:27], v[26:27], 0, s[8:9]
	v_add_u32_e32 v31, s4, v20
	v_add_u32_e32 v30, 6, v31
	v_add_u32_e32 v32, 8, v31
	v_add_u32_e32 v34, 10, v31
	v_add_u32_e32 v50, 12, v31
	v_add_u32_e32 v52, 14, v31
	v_ashrrev_i32_e32 v31, 31, v30
	v_ashrrev_i32_e32 v33, 31, v32
	v_ashrrev_i32_e32 v35, 31, v34
	v_ashrrev_i32_e32 v51, 31, v50
	v_ashrrev_i32_e32 v53, 31, v52
	v_lshlrev_b64 v[30:31], 12, v[30:31]
	v_lshlrev_b64 v[32:33], 12, v[32:33]
	v_lshlrev_b64 v[34:35], 12, v[34:35]
	v_lshlrev_b64 v[50:51], 12, v[50:51]
	v_lshlrev_b64 v[52:53], 12, v[52:53]
	v_lshl_add_u64 v[30:31], v[28:29], 0, v[30:31]
	v_lshl_add_u64 v[32:33], v[28:29], 0, v[32:33]
	v_lshl_add_u64 v[34:35], v[28:29], 0, v[34:35]
	global_load_dword v192, v[26:27], off nt
	global_load_dword v193, v[24:25], off nt
	global_load_dword v194, v[22:23], off nt
	v_lshl_add_u64 v[50:51], v[28:29], 0, v[50:51]
	v_lshl_add_u64 v[52:53], v[28:29], 0, v[52:53]
	global_load_dword v195, v[30:31], off nt
	global_load_dword v196, v[32:33], off nt
	global_load_dword v197, v[34:35], off nt
	global_load_dword v198, v[50:51], off nt
	global_load_dword v199, v[52:53], off nt
	s_add_i32 s4, s4, 16
	v_lshl_add_u64 v[22:23], v[22:23], 0, s[8:9]
	v_lshl_add_u64 v[24:25], v[24:25], 0, s[8:9]
	v_lshl_add_u64 v[26:27], v[26:27], 0, s[8:9]
	v_add_u32_e32 v31, s4, v20
	v_add_u32_e32 v30, 6, v31
	v_add_u32_e32 v32, 8, v31
	v_add_u32_e32 v34, 10, v31
	v_add_u32_e32 v50, 12, v31
	v_add_u32_e32 v52, 14, v31
	v_ashrrev_i32_e32 v31, 31, v30
	v_ashrrev_i32_e32 v33, 31, v32
	v_ashrrev_i32_e32 v35, 31, v34
	v_ashrrev_i32_e32 v51, 31, v50
	v_ashrrev_i32_e32 v53, 31, v52
	v_lshlrev_b64 v[30:31], 12, v[30:31]
	v_lshlrev_b64 v[32:33], 12, v[32:33]
	v_lshlrev_b64 v[34:35], 12, v[34:35]
	v_lshlrev_b64 v[50:51], 12, v[50:51]
	v_lshlrev_b64 v[52:53], 12, v[52:53]
	v_lshl_add_u64 v[30:31], v[28:29], 0, v[30:31]
	v_lshl_add_u64 v[32:33], v[28:29], 0, v[32:33]
	v_lshl_add_u64 v[34:35], v[28:29], 0, v[34:35]
	global_load_dword v200, v[26:27], off nt
	global_load_dword v201, v[24:25], off nt
	global_load_dword v202, v[22:23], off nt
	v_lshl_add_u64 v[50:51], v[28:29], 0, v[50:51]
	v_lshl_add_u64 v[52:53], v[28:29], 0, v[52:53]
	global_load_dword v203, v[30:31], off nt
	global_load_dword v204, v[32:33], off nt
	global_load_dword v205, v[34:35], off nt
	global_load_dword v206, v[50:51], off nt
	global_load_dword v207, v[52:53], off nt
	s_add_i32 s4, s4, 16
	v_lshl_add_u64 v[22:23], v[22:23], 0, s[8:9]
	v_lshl_add_u64 v[24:25], v[24:25], 0, s[8:9]
	v_lshl_add_u64 v[26:27], v[26:27], 0, s[8:9]
	s_waitcnt vmcnt(24)
; #define LAS __attribute__((address_space(3)))
; __device__ __forceinline__ unsigned cvtpk(float lo, float hi) { f32x2_t v = {lo, hi}; bf16x2_t b = __builtin_convertvector(v, bf16x2_t); return __builtin_bit_cast(unsigned, b); }
; __device__ __forceinline__ void tr_item(const float* W, int N, int k0, int n0, bf16* WT, int dst_pitch, int dst_row0, int dst_k0, int ncopies, int copy_stride, LAS float* scr, int lane) {
;     ...
;     for (int i = 0; i < 32; ++i) { const int kk = 2 * i + (lane >> 5); scr[kk * 33 + (lane & 31)] = __builtin_nontemporal_load(W + (size_t)(k0 + kk) * N + n0 + (lane & 31)); }
;     asm volatile("s_waitcnt lgkmcnt(0)" ::: "memory");
;     const int c = lane & 7;
; #pragma unroll
;     for (int j = 0; j < 4; ++j) { const int n = (lane >> 3) + 8 * j; const LAS float* s = scr + (8 * c) * 33 + n;
;         u32x4 o; o.x = cvtpk(s[0 * 33], s[1 * 33]); o.y = cvtpk(s[2 * 33], s[3 * 33]); o.z = cvtpk(s[4 * 33], s[5 * 33]); o.w = cvtpk(s[6 * 33], s[7 * 33]);
;         bf16* dst = WT + (size_t)(dst_row0 + n0 + n) * dst_pitch + dst_k0 + k0 + 8 * c;
;         for (int cp = 0; cp < ncopies; ++cp) *(u32x4*)(dst + (size_t)cp * copy_stride) = o; }
	v_add_u32_e32 v35, 0x400, v19
	ds_write2_b32 v19, v176, v177 offset1:66
	ds_write2_b32 v19, v178, v179 offset0:132 offset1:198
	ds_write2_b32 v35, v180, v181 offset0:8 offset1:74
	ds_write2_b32 v35, v182, v183 offset0:140 offset1:206
	v_add_u32_e32 v19, 0x840, v19
	s_waitcnt vmcnt(16)
	v_add_u32_e32 v35, 0x400, v19
	ds_write2_b32 v19, v184, v185 offset1:66
	ds_write2_b32 v19, v186, v187 offset0:132 offset1:198
	ds_write2_b32 v35, v188, v189 offset0:8 offset1:74
	ds_write2_b32 v35, v190, v191 offset0:140 offset1:206
	v_add_u32_e32 v19, 0x840, v19
	s_waitcnt vmcnt(8)
	v_add_u32_e32 v35, 0x400, v19
	ds_write2_b32 v19, v192, v193 offset1:66
	ds_write2_b32 v19, v194, v195 offset0:132 offset1:198
	ds_write2_b32 v35, v196, v197 offset0:8 offset1:74
	ds_write2_b32 v35, v198, v199 offset0:140 offset1:206
	v_add_u32_e32 v19, 0x840, v19
	s_waitcnt vmcnt(0)
	v_add_u32_e32 v35, 0x400, v19
	ds_write2_b32 v19, v200, v201 offset1:66
	ds_write2_b32 v19, v202, v203 offset0:132 offset1:198
	ds_write2_b32 v35, v204, v205 offset0:8 offset1:74
	ds_write2_b32 v35, v206, v207 offset0:140 offset1:206
	v_add_u32_e32 v19, 0x840, v19
	s_waitcnt lgkmcnt(0)
	s_lshl_b32 s4, s27, 1
	ds_read2_b32 v[24:25], v37 offset0:33 offset1:41
	ds_read2_b32 v[26:27], v37 offset1:8
	ds_read2_b32 v[28:29], v37 offset0:66 offset1:74
	ds_read2_b32 v[30:31], v37 offset0:99 offset1:107
	ds_read2_b32 v[32:33], v37 offset0:132 offset1:140
	ds_read2_b32 v[34:35], v37 offset0:165 offset1:173
	ds_read2_b32 v[50:51], v37 offset0:198 offset1:206
	ds_read2_b32 v[52:53], v37 offset0:231 offset1:239
	s_add_i32 s4, s4, 0x7fffee00
	s_and_b32 s4, s4, 0x7fffffc0
	v_add_u32_e32 v56, s20, v36
	s_lshl_b32 s4, s4, 1
	v_ashrrev_i32_e32 v57, 31, v56
	v_lshl_add_u64 v[54:55], v[10:11], 0, s[4:5]
	v_lshlrev_b64 v[56:57], 11, v[56:57]
	s_waitcnt lgkmcnt(6)
	v_cvt_pk_bf16_f32 v20, v26, v24
	s_waitcnt lgkmcnt(4)
	v_cvt_pk_bf16_f32 v21, v28, v30
	s_waitcnt lgkmcnt(2)
	v_cvt_pk_bf16_f32 v22, v32, v34
	s_waitcnt lgkmcnt(0)
	v_cvt_pk_bf16_f32 v23, v50, v52
	v_lshl_add_u64 v[56:57], v[54:55], 0, v[56:57]
	v_add_u32_e32 v24, s20, v38
	global_store_dwordx4 v[56:57], v[20:23], off
	s_nop 1
	v_cvt_pk_bf16_f32 v20, v27, v25
	v_ashrrev_i32_e32 v25, 31, v24
	v_cvt_pk_bf16_f32 v21, v29, v31
	v_cvt_pk_bf16_f32 v22, v33, v35
	v_cvt_pk_bf16_f32 v23, v51, v53
	v_lshlrev_b64 v[24:25], 11, v[24:25]
	ds_read2_b32 v[26:27], v37 offset0:49 offset1:57
	ds_read2_b32 v[28:29], v37 offset0:16 offset1:24
	ds_read2_b32 v[30:31], v37 offset0:82 offset1:90
	ds_read2_b32 v[32:33], v37 offset0:115 offset1:123
	ds_read2_b32 v[34:35], v37 offset0:148 offset1:156
	ds_read2_b32 v[50:51], v37 offset0:181 offset1:189
	ds_read2_b32 v[52:53], v37 offset0:214 offset1:222
	ds_read2_b32 v[56:57], v37 offset0:247 offset1:255
	v_lshl_add_u64 v[24:25], v[54:55], 0, v[24:25]
	global_store_dwordx4 v[24:25], v[20:23], off
	v_add_u32_e32 v24, s20, v39
	v_ashrrev_i32_e32 v25, 31, v24
	v_lshlrev_b64 v[24:25], 11, v[24:25]
	s_waitcnt lgkmcnt(6)
	v_cvt_pk_bf16_f32 v20, v28, v26
	s_waitcnt lgkmcnt(4)
	v_cvt_pk_bf16_f32 v21, v30, v32
	s_waitcnt lgkmcnt(2)
	v_cvt_pk_bf16_f32 v22, v34, v50
	s_waitcnt lgkmcnt(0)
	v_cvt_pk_bf16_f32 v23, v52, v56
	v_lshl_add_u64 v[24:25], v[54:55], 0, v[24:25]
	global_store_dwordx4 v[24:25], v[20:23], off
	v_add_u32_e32 v24, s20, v40
	v_ashrrev_i32_e32 v25, 31, v24
	v_lshlrev_b64 v[24:25], 11, v[24:25]
	v_cvt_pk_bf16_f32 v20, v29, v27
	v_cvt_pk_bf16_f32 v21, v31, v33
	v_cvt_pk_bf16_f32 v22, v35, v51
	v_cvt_pk_bf16_f32 v23, v53, v57
	v_lshl_add_u64 v[24:25], v[54:55], 0, v[24:25]
	global_store_dwordx4 v[24:25], v[20:23], off
	s_waitcnt lgkmcnt(0)
